# grid-barrier wait: three staggered polls of the release flag kept in flight ahead of the compiled poll loop (fallback after 4096 rounds)
# speedup vs baseline: 1.0025x; 1.0010x over previous
; __device__ __forceinline__ unsigned xb_ld(unsigned* p)              { return __hip_atomic_load(p, __ATOMIC_RELAXED, __HIP_MEMORY_SCOPE_AGENT); }
; #define XB_SPIN(cond, bar) do { unsigned _sp = 0; while (cond) { __builtin_amdgcn_s_sleep(1); \
;     if ((++_sp & 255u) == 0u) { if (xb_ld(&(bar)[XB_TMO])) break; if (_sp > XB_SPIN_CAP) { atomicAdd(&(bar)[XB_TMO], 1u); break; } } } } while (0)
; __device__ __forceinline__ void xcd_barrier(const XcdBarrier& b) {
;     ...
;         XB_SPIN(xb_ld(&bar[XB_XGEN(bx_)]) < (gen + 1u) * nx, bar);
;         __builtin_amdgcn_fence(__ATOMIC_ACQUIRE, "agent");
;         asm volatile("s_waitcnt vmcnt(0)" ::: "memory");
.LBB0_730:
	s_or_b64 exec, exec, s[0:1]
	s_add_i32 s84, s4, 0x900
	s_lshl_b64 s[0:1], s[84:85], 2
	s_add_u32 s0, s34, s0
	s_addc_u32 s1, s35, s1
	v_mul_lo_u32 v2, v5, v2
	v_mov_b64_e32 v[4:5], s[0:1]
	s_movk_i32 s2, 0x1000
	global_load_dword v6, v[4:5], off sc1
	s_sleep 10
	global_load_dword v7, v[4:5], off sc1
	s_sleep 10
	global_load_dword v8, v[4:5], off sc1
.Lpp0_loop:
	s_waitcnt vmcnt(2)
	v_cmp_ge_u32_e32 vcc, v6, v2
	s_cbranch_vccnz .Lpp0_hit
	global_load_dword v6, v[4:5], off sc1
	s_waitcnt vmcnt(2)
	v_cmp_ge_u32_e32 vcc, v7, v2
	s_cbranch_vccnz .Lpp0_hit
	global_load_dword v7, v[4:5], off sc1
	s_waitcnt vmcnt(2)
	v_cmp_ge_u32_e32 vcc, v8, v2
	s_cbranch_vccnz .Lpp0_hit
	global_load_dword v8, v[4:5], off sc1
	s_sub_u32 s2, s2, 1
	s_cmp_lg_u32 s2, 0
	s_cbranch_scc1 .Lpp0_loop
	s_branch .Lpp0_miss
.Lpp0_hit:
	s_mov_b64 s[2:3], exec
	s_branch .LBB0_741
.Lpp0_miss:
	flat_load_dword v4, v[4:5] sc1
	s_waitcnt vmcnt(0) lgkmcnt(0)
	v_cmp_lt_u32_e32 vcc, v4, v2
	s_and_saveexec_b64 s[2:3], vcc
	s_cbranch_execz .LBB0_741
	s_mov_b32 s18, 1
	s_mov_b64 s[4:5], 0
	s_branch .LBB0_733

; __device__ __forceinline__ unsigned xb_ld(unsigned* p)              { return __hip_atomic_load(p, __ATOMIC_RELAXED, __HIP_MEMORY_SCOPE_AGENT); }
; #define XB_SPIN(cond, bar) do { unsigned _sp = 0; while (cond) { __builtin_amdgcn_s_sleep(1); \
;     if ((++_sp & 255u) == 0u) { if (xb_ld(&(bar)[XB_TMO])) break; if (_sp > XB_SPIN_CAP) { atomicAdd(&(bar)[XB_TMO], 1u); break; } } } } while (0)
; __device__ __forceinline__ void xcd_barrier(const XcdBarrier& b) {
;     ...
;         XB_SPIN(xb_ld(&bar[XB_XGEN(bx_)]) < (gen + 1u) * nx, bar);
;         __builtin_amdgcn_fence(__ATOMIC_ACQUIRE, "agent");
;         asm volatile("s_waitcnt vmcnt(0)" ::: "memory");
.Lpp6_miss:
	flat_load_dword v4, v[4:5] sc1
	s_waitcnt vmcnt(0) lgkmcnt(0)
	v_cmp_lt_u32_e32 vcc, v4, v2
	s_and_saveexec_b64 s[2:3], vcc
	s_cbranch_execnz .LBB0_2151
.Lpp6_far:
	s_getpc_b64 s[98:99]
